# baseline (speedup 1.0000x reference)
.Lattn_head:
.LBB0_174:
	ds_read_b128 v[8:11], v206 offset:0
	s_add_i32 s91, s82, s89
	v_lshl_add_u32 v208, s0, 15, v180
	ds_read_b128 v[4:7], v206 offset:0x400
	s_add_i32 s28, s89, 0xffffff80
	s_add_i32 s2, s91, 0xffffff80
	s_add_i32 s0, s91, 0xffffff9f
	ds_read_b64_tr_b16 v[136:137], v208 offset:0
	s_cmp_gt_i32 s0, s86
	ds_read_b64_tr_b16 v[138:139], v208 offset:0x800
	s_cselect_b64 s[8:9], -1, 0
	s_cmp_lt_i32 s2, s87
	ds_read_b64_tr_b16 v[140:141], v208 offset:0x200
	s_cselect_b64 s[0:1], -1, 0
	s_cmp_ge_i32 s2, s87
	ds_read_b64_tr_b16 v[142:143], v208 offset:0xa00
	s_cselect_b64 s[2:3], -1, 0
	ds_read_b64_tr_b16 v[12:13], v208 offset:0x400
	s_and_b64 vcc, s[8:9], s[2:3]
	ds_read_b64_tr_b16 v[14:15], v208 offset:0xc00
	v_cndmask_b32_e32 v0, 0, v183, vcc
	v_cndmask_b32_e32 v1, 0, v184, vcc
	ds_read_b64_tr_b16 v[132:133], v208 offset:0x600
	v_cndmask_b32_e64 v0, v181, v0, s[8:9]
	v_cndmask_b32_e64 v1, v182, v1, s[8:9]
	v_mov_b32_e32 v2, v3
	ds_read_b64_tr_b16 v[134:135], v208 offset:0xe00
	ds_read_b128 v[210:213], v186 offset:0
	ds_read_b128 v[214:217], v187 offset:0
	ds_read_b128 v[218:221], v188 offset:0
	ds_read_b128 v[222:225], v189 offset:0
	s_nop 1
	v_mfma_f32_32x32x16_bf16 v[80:95], v[128:131], v[0:3], 0
	s_add_i32 m0, s83, 0x1c000
	s_nop 0
	global_load_lds_dwordx4 v242, s[74:75]
	s_waitcnt lgkmcnt(3)
	v_mfma_f32_32x32x16_bf16 v[80:95], v[210:213], v[96:99], v[80:95]
	ds_read_b128 v[210:213], v186 offset:0x80
	s_add_i32 m0, s83, 0x1c400
	s_nop 0
	global_load_lds_dwordx4 v243, s[74:75]
	s_waitcnt lgkmcnt(3)
	v_mfma_f32_32x32x16_bf16 v[80:95], v[214:217], v[100:103], v[80:95]
	v_cvt_f32_u32_e32 v0, s28
	v_sub_f32_e32 v1, v185, v0
	v_cndmask_b32_e64 v0, -v148, v148, s[8:9]
	v_mul_f32_e32 v0, v1, v0
	ds_read_b128 v[214:217], v187 offset:0x80
	s_waitcnt lgkmcnt(3)
	v_mfma_f32_32x32x16_bf16 v[80:95], v[218:221], v[104:107], v[80:95]
	ds_read_b128 v[218:221], v188 offset:0x80
	s_waitcnt lgkmcnt(3)
	v_mfma_f32_32x32x16_bf16 v[80:95], v[222:225], v[108:111], v[80:95]
	ds_read_b128 v[222:225], v189 offset:0x80
	s_waitcnt lgkmcnt(3)
	v_mfma_f32_32x32x16_bf16 v[80:95], v[210:213], v[112:115], v[80:95]
	s_waitcnt lgkmcnt(2)
	v_mfma_f32_32x32x16_bf16 v[80:95], v[214:217], v[116:119], v[80:95]
	s_waitcnt lgkmcnt(1)
	v_mfma_f32_32x32x16_bf16 v[80:95], v[218:221], v[120:123], v[80:95]
	s_waitcnt lgkmcnt(0)
	v_mfma_f32_32x32x16_bf16 v[80:95], v[222:225], v[124:127], v[80:95]
	s_and_b64 vcc, s[8:9], s[0:1]
	s_cbranch_vccz .LBB0_178
	v_sub_f32_e32 v0, v1, v201
	s_mov_b32 s0, -2.0
	v_add_f32_e32 v1, -1.0, v0
	s_mov_b32 s1, 0xc0400000
	v_pk_add_f32 v[210:211], v[0:1], s[0:1] op_sel_hi:[0,1]
	s_mov_b32 s0, 0xc1000000
	s_mov_b32 s1, 0xc1100000
	v_pk_add_f32 v[212:213], v[0:1], s[0:1] op_sel_hi:[0,1]
	s_mov_b32 s0, 0xc1200000
	s_mov_b32 s1, 0xc1300000
	v_pk_add_f32 v[214:215], v[0:1], s[0:1] op_sel_hi:[0,1]
	s_mov_b32 s0, 0xc1800000
	s_mov_b32 s1, 0xc1880000
	v_pk_add_f32 v[216:217], v[0:1], s[0:1] op_sel_hi:[0,1]
	s_mov_b32 s0, 0xc1900000
	s_mov_b32 s1, 0xc1980000
	v_pk_add_f32 v[218:219], v[0:1], s[0:1] op_sel_hi:[0,1]
	v_pk_add_f32 v[220:221], v[0:1], s[34:35] op_sel_hi:[0,1]
	v_pk_add_f32 v[222:223], v[0:1], s[36:37] op_sel_hi:[0,1]
	v_and_b32_e32 v211, 0x7fffffff, v211
	v_and_b32_e32 v210, 0x7fffffff, v210
	v_and_b32_e32 v213, 0x7fffffff, v213
	v_and_b32_e32 v212, 0x7fffffff, v212
	v_and_b32_e32 v215, 0x7fffffff, v215
	v_and_b32_e32 v214, 0x7fffffff, v214
	v_and_b32_e32 v217, 0x7fffffff, v217
	v_and_b32_e32 v216, 0x7fffffff, v216
	v_and_b32_e32 v219, 0x7fffffff, v219
	v_and_b32_e32 v218, 0x7fffffff, v218
	v_and_b32_e32 v221, 0x7fffffff, v221
	v_and_b32_e32 v220, 0x7fffffff, v220
	v_and_b32_e32 v223, 0x7fffffff, v223
	v_and_b32_e32 v222, 0x7fffffff, v222
	v_and_b32_e32 v0, 0x7fffffff, v0
	v_and_b32_e32 v1, 0x7fffffff, v1
	v_mov_b32_e32 v159, v158
	v_pk_fma_f32 v[94:95], v[158:159], v[222:223], v[94:95]
	v_pk_fma_f32 v[92:93], v[158:159], v[220:221], v[92:93]
	v_pk_fma_f32 v[90:91], v[158:159], v[218:219], v[90:91]
	v_pk_fma_f32 v[88:89], v[158:159], v[216:217], v[88:89]
	v_pk_fma_f32 v[86:87], v[158:159], v[214:215], v[86:87]
	v_pk_fma_f32 v[84:85], v[158:159], v[212:213], v[84:85]
	v_pk_fma_f32 v[82:83], v[158:159], v[210:211], v[82:83]
	v_pk_fma_f32 v[80:81], v[160:161], v[0:1], v[80:81]
	v_mov_b32_e32 v0, 0
.LBB0_178:
	v_sub_f32_e32 v0, v0, v203
	v_mul_f32_e32 v0, 0x3e0293ee, v0
	s_waitcnt lgkmcnt(4)
	v_mfma_f32_32x32x16_bf16 v[32:47], v[8:11], v[136:139], v[32:47]
	ds_read_b64_tr_b16 v[136:137], v208 offset:0x1000
	ds_read_b64_tr_b16 v[138:139], v208 offset:0x1800
	v_mfma_f32_32x32x16_bf16 v[16:31], v[8:11], v[140:143], v[16:31]
	ds_read_b64_tr_b16 v[140:141], v208 offset:0x1200
	ds_read_b64_tr_b16 v[142:143], v208 offset:0x1a00
	s_waitcnt lgkmcnt(4)
	v_fmamk_f32 v1, v80, 0x3e0293ee, v0
	v_exp_f32_e32 v209, v1
	v_fmamk_f32 v1, v81, 0x3e0293ee, v0
	v_exp_f32_e32 v210, v1
	v_mfma_f32_32x32x16_bf16 v[64:79], v[8:11], v[12:15], v[64:79]
	v_fmamk_f32 v1, v82, 0x3e0293ee, v0
	v_exp_f32_e32 v211, v1
	v_mfma_f32_32x32x16_bf16 v[48:63], v[8:11], v[132:135], v[48:63]
	s_mov_b32 m0, s97
	s_nop 0
	global_load_lds_dwordx4 v244, s[76:77]
	ds_read_b128 v[8:11], v206 offset:0x800
	ds_read_b64_tr_b16 v[12:13], v208 offset:0x1400
	ds_read_b64_tr_b16 v[14:15], v208 offset:0x1c00
	ds_read_b64_tr_b16 v[132:133], v208 offset:0x1600
	ds_read_b64_tr_b16 v[134:135], v208 offset:0x1e00
	v_fmamk_f32 v1, v83, 0x3e0293ee, v0
	v_exp_f32_e32 v212, v1
	s_waitcnt lgkmcnt(5)
	v_mfma_f32_32x32x16_bf16 v[32:47], v[4:7], v[136:139], v[32:47]
	ds_read_b64_tr_b16 v[136:137], v208 offset:0x2000
	ds_read_b64_tr_b16 v[138:139], v208 offset:0x2800
	v_fmamk_f32 v1, v84, 0x3e0293ee, v0
	v_exp_f32_e32 v213, v1
	v_mfma_f32_32x32x16_bf16 v[16:31], v[4:7], v[140:143], v[16:31]
	s_add_i32 m0, s97, 0x400
	s_nop 0
	global_load_lds_dwordx4 v245, s[76:77]
	ds_read_b64_tr_b16 v[140:141], v208 offset:0x2200
	ds_read_b64_tr_b16 v[142:143], v208 offset:0x2a00
	v_fmamk_f32 v1, v85, 0x3e0293ee, v0
	v_exp_f32_e32 v214, v1
	s_waitcnt lgkmcnt(4)
	v_mfma_f32_32x32x16_bf16 v[64:79], v[4:7], v[12:15], v[64:79]
	v_fmamk_f32 v1, v86, 0x3e0293ee, v0
	v_exp_f32_e32 v215, v1
	v_mfma_f32_32x32x16_bf16 v[48:63], v[4:7], v[132:135], v[48:63]
	s_add_i32 m0, s97, 0x4000
	s_nop 0
	global_load_lds_dwordx4 v246, s[76:77]
	ds_read_b128 v[4:7], v206 offset:0xc00
	ds_read_b64_tr_b16 v[12:13], v208 offset:0x2400
	ds_read_b64_tr_b16 v[14:15], v208 offset:0x2c00
	ds_read_b64_tr_b16 v[132:133], v208 offset:0x2600
	ds_read_b64_tr_b16 v[134:135], v208 offset:0x2e00
	v_fmamk_f32 v1, v87, 0x3e0293ee, v0
	v_exp_f32_e32 v216, v1
	s_waitcnt lgkmcnt(5)
	v_mfma_f32_32x32x16_bf16 v[32:47], v[8:11], v[136:139], v[32:47]
	ds_read_b64_tr_b16 v[136:137], v208 offset:0x3000
	ds_read_b64_tr_b16 v[138:139], v208 offset:0x3800
	v_fmamk_f32 v1, v88, 0x3e0293ee, v0
	v_exp_f32_e32 v217, v1
	v_mfma_f32_32x32x16_bf16 v[16:31], v[8:11], v[140:143], v[16:31]
	s_add_i32 m0, s97, 0x4400
	s_nop 0
	global_load_lds_dwordx4 v247, s[76:77]
	ds_read_b64_tr_b16 v[140:141], v208 offset:0x3200
	ds_read_b64_tr_b16 v[142:143], v208 offset:0x3a00
	v_fmamk_f32 v1, v89, 0x3e0293ee, v0
	v_exp_f32_e32 v218, v1
	s_waitcnt lgkmcnt(4)
	v_mfma_f32_32x32x16_bf16 v[64:79], v[8:11], v[12:15], v[64:79]
	v_fmamk_f32 v1, v90, 0x3e0293ee, v0
	v_exp_f32_e32 v219, v1
	v_mfma_f32_32x32x16_bf16 v[48:63], v[8:11], v[132:135], v[48:63]
	ds_read_b64_tr_b16 v[8:9], v208 offset:0x3400
	ds_read_b64_tr_b16 v[10:11], v208 offset:0x3c00
	ds_read_b64_tr_b16 v[12:13], v208 offset:0x3600
	ds_read_b64_tr_b16 v[14:15], v208 offset:0x3e00
	v_fmamk_f32 v1, v91, 0x3e0293ee, v0
	v_exp_f32_e32 v220, v1
	s_waitcnt lgkmcnt(4)
	v_mfma_f32_32x32x16_bf16 v[32:47], v[4:7], v[136:139], v[32:47]
	v_fmamk_f32 v1, v92, 0x3e0293ee, v0
	v_exp_f32_e32 v221, v1
	v_fmamk_f32 v1, v93, 0x3e0293ee, v0
	v_exp_f32_e32 v222, v1
	s_waitcnt lgkmcnt(0)
	v_mfma_f32_32x32x16_bf16 v[16:31], v[4:7], v[140:143], v[16:31]
	v_fmamk_f32 v1, v94, 0x3e0293ee, v0
	v_fmac_f32_e32 v0, 0x3e0293ee, v95
	v_exp_f32_e32 v223, v1
	v_exp_f32_e32 v224, v0
	v_cvt_pk_bf16_f32 v248, v209, v210
	v_cvt_pk_bf16_f32 v249, v211, v212
	v_cvt_pk_bf16_f32 v250, v213, v214
	v_cvt_pk_bf16_f32 v251, v215, v216
	v_mfma_f32_32x32x16_bf16 v[64:79], v[4:7], v[8:11], v[64:79]
	s_add_i32 s0, s88, 1
	s_nop 0
	v_permlane32_swap_b32_e32 v248, v250
	v_permlane32_swap_b32_e32 v249, v251
	ds_write_b128 v204, v[248:251]
	v_cvt_pk_bf16_f32 v248, v217, v218
	v_cvt_pk_bf16_f32 v249, v219, v220
	v_cvt_pk_bf16_f32 v250, v221, v222
	v_cvt_pk_bf16_f32 v251, v223, v224
	v_mfma_f32_32x32x16_bf16 v[48:63], v[4:7], v[12:15], v[48:63]
	s_cmp_lg_u32 s88, 2
	s_nop 0
	v_permlane32_swap_b32_e32 v248, v250
	v_permlane32_swap_b32_e32 v249, v251
	ds_write_b128 v204, v[248:251] offset:1024
	s_cselect_b32 s28, s0, 0
	s_cmp_ge_i32 s90, s80
	s_cselect_b64 s[2:3], -1, 0
	s_lshl_b32 s98, s80, 6
	s_sub_i32 s98, s98, 64
	s_min_i32 s96, s89, s98
	s_mul_i32 s96, s96, 0x6000
	s_lshl_b32 s97, s28, 15
	s_add_i32 s97, s83, s97
	v_add_u32_e32 v242, s96, v150
	v_add_u32_e32 v243, s96, v154
	v_add_u32_e32 v244, s96, v152
	v_add_u32_e32 v245, s96, v156
	v_add_u32_e32 v246, 0x100, v244
	v_add_u32_e32 v247, 0x100, v245
	s_waitcnt vmcnt(4) lgkmcnt(0)
	s_barrier
.LBB0_180:
	ds_read_b128 v[8:11], v202 offset:0
	v_lshl_add_u32 v208, s29, 15, v180
	ds_read_b128 v[4:7], v202 offset:0x400
	s_sub_i32 s29, s89, 64
	s_sub_i32 s92, s91, 64
	s_sub_i32 s0, s91, 33
	ds_read_b64_tr_b16 v[136:137], v208 offset:0
	s_cmp_gt_i32 s0, s86
	ds_read_b64_tr_b16 v[138:139], v208 offset:0x800
	s_cselect_b64 s[8:9], -1, 0
	s_cmp_lt_i32 s92, s87
	ds_read_b64_tr_b16 v[140:141], v208 offset:0x200
	s_cselect_b64 s[0:1], -1, 0
	s_cmp_ge_i32 s92, s87
	ds_read_b64_tr_b16 v[142:143], v208 offset:0xa00
	s_cselect_b64 s[92:93], -1, 0
	ds_read_b64_tr_b16 v[12:13], v208 offset:0x400
	s_and_b64 vcc, s[8:9], s[92:93]
	ds_read_b64_tr_b16 v[14:15], v208 offset:0xc00
	v_cndmask_b32_e32 v0, 0, v183, vcc
	v_cndmask_b32_e32 v1, 0, v184, vcc
	ds_read_b64_tr_b16 v[132:133], v208 offset:0x600
	v_cndmask_b32_e64 v0, v181, v0, s[8:9]
	v_cndmask_b32_e64 v1, v182, v1, s[8:9]
	v_mov_b32_e32 v2, v3
	ds_read_b64_tr_b16 v[134:135], v208 offset:0xe00
	ds_read_b128 v[226:229], v186 offset:0x4000
	ds_read_b128 v[230:233], v187 offset:0x4000
	ds_read_b128 v[234:237], v188 offset:0x4000
	ds_read_b128 v[238:241], v189 offset:0x4000
	s_nop 1
	v_mfma_f32_32x32x16_bf16 v[80:95], v[128:131], v[0:3], 0
	s_mov_b32 m0, s84
	s_nop 0
	global_load_lds_dwordx4 v242, s[74:75]
	s_waitcnt lgkmcnt(3)
	v_mfma_f32_32x32x16_bf16 v[80:95], v[226:229], v[96:99], v[80:95]
	v_add_f32_e32 v254, 0, v209
	v_add_f32_e32 v254, v210, v254
	ds_read_b128 v[226:229], v186 offset:0x4080
	s_mov_b32 m0, s85
	s_nop 0
	global_load_lds_dwordx4 v243, s[74:75]
	s_waitcnt lgkmcnt(3)
	v_mfma_f32_32x32x16_bf16 v[80:95], v[230:233], v[100:103], v[80:95]
	v_cvt_f32_u32_e32 v0, s29
	v_sub_f32_e32 v0, v185, v0
	v_cndmask_b32_e64 v1, -v148, v148, s[8:9]
	v_mul_f32_e32 v1, v0, v1
	v_add_f32_e32 v254, v211, v254
	v_add_f32_e32 v254, v212, v254
	ds_read_b128 v[230:233], v187 offset:0x4080
	s_waitcnt lgkmcnt(3)
	v_mfma_f32_32x32x16_bf16 v[80:95], v[234:237], v[104:107], v[80:95]
	v_add_f32_e32 v254, v213, v254
	v_add_f32_e32 v254, v214, v254
	ds_read_b128 v[234:237], v188 offset:0x4080
	s_waitcnt lgkmcnt(3)
	v_mfma_f32_32x32x16_bf16 v[80:95], v[238:241], v[108:111], v[80:95]
	v_add_f32_e32 v254, v215, v254
	v_add_f32_e32 v254, v216, v254
	ds_read_b128 v[238:241], v189 offset:0x4080
	s_waitcnt lgkmcnt(3)
	v_mfma_f32_32x32x16_bf16 v[80:95], v[226:229], v[112:115], v[80:95]
	v_add_f32_e32 v254, v217, v254
	v_add_f32_e32 v254, v218, v254
	s_waitcnt lgkmcnt(2)
	v_mfma_f32_32x32x16_bf16 v[80:95], v[230:233], v[116:119], v[80:95]
	v_add_f32_e32 v254, v219, v254
	v_add_f32_e32 v254, v220, v254
	s_waitcnt lgkmcnt(1)
	v_mfma_f32_32x32x16_bf16 v[80:95], v[234:237], v[120:123], v[80:95]
	v_add_f32_e32 v254, v221, v254
	v_add_f32_e32 v254, v222, v254
	s_waitcnt lgkmcnt(0)
	v_mfma_f32_32x32x16_bf16 v[80:95], v[238:241], v[124:127], v[80:95]
	v_add_f32_e32 v254, v223, v254
	v_add_f32_e32 v254, v224, v254
	s_and_b64 vcc, s[8:9], s[0:1]
	s_cbranch_vccz .LBB0_184
	v_sub_f32_e32 v0, v0, v201
	s_mov_b32 s0, -2.0
	v_add_f32_e32 v1, -1.0, v0
	s_mov_b32 s1, 0xc0400000
	v_pk_add_f32 v[226:227], v[0:1], s[0:1] op_sel_hi:[0,1]
	s_mov_b32 s0, 0xc1000000
	s_mov_b32 s1, 0xc1100000
	v_pk_add_f32 v[228:229], v[0:1], s[0:1] op_sel_hi:[0,1]
	s_mov_b32 s0, 0xc1200000
	s_mov_b32 s1, 0xc1300000
	v_pk_add_f32 v[230:231], v[0:1], s[0:1] op_sel_hi:[0,1]
	s_mov_b32 s0, 0xc1800000
	s_mov_b32 s1, 0xc1880000
	v_pk_add_f32 v[232:233], v[0:1], s[0:1] op_sel_hi:[0,1]
	s_mov_b32 s0, 0xc1900000
	s_mov_b32 s1, 0xc1980000
	v_pk_add_f32 v[234:235], v[0:1], s[0:1] op_sel_hi:[0,1]
	v_pk_add_f32 v[236:237], v[0:1], s[34:35] op_sel_hi:[0,1]
	v_pk_add_f32 v[238:239], v[0:1], s[36:37] op_sel_hi:[0,1]
	v_and_b32_e32 v227, 0x7fffffff, v227
	v_and_b32_e32 v226, 0x7fffffff, v226
	v_and_b32_e32 v229, 0x7fffffff, v229
	v_and_b32_e32 v228, 0x7fffffff, v228
	v_and_b32_e32 v231, 0x7fffffff, v231
	v_and_b32_e32 v230, 0x7fffffff, v230
	v_and_b32_e32 v233, 0x7fffffff, v233
	v_and_b32_e32 v232, 0x7fffffff, v232
	v_and_b32_e32 v235, 0x7fffffff, v235
	v_and_b32_e32 v234, 0x7fffffff, v234
	v_and_b32_e32 v237, 0x7fffffff, v237
	v_and_b32_e32 v236, 0x7fffffff, v236
	v_and_b32_e32 v239, 0x7fffffff, v239
	v_and_b32_e32 v238, 0x7fffffff, v238
	v_and_b32_e32 v0, 0x7fffffff, v0
	v_and_b32_e32 v1, 0x7fffffff, v1
	v_mov_b32_e32 v159, v158
	v_pk_fma_f32 v[94:95], v[158:159], v[238:239], v[94:95]
	v_pk_fma_f32 v[92:93], v[158:159], v[236:237], v[92:93]
	v_pk_fma_f32 v[90:91], v[158:159], v[234:235], v[90:91]
	v_pk_fma_f32 v[88:89], v[158:159], v[232:233], v[88:89]
	v_pk_fma_f32 v[86:87], v[158:159], v[230:231], v[86:87]
	v_pk_fma_f32 v[84:85], v[158:159], v[228:229], v[84:85]
	v_pk_fma_f32 v[82:83], v[158:159], v[226:227], v[82:83]
	v_pk_fma_f32 v[80:81], v[160:161], v[0:1], v[80:81]
	v_mov_b32_e32 v1, 0
.LBB0_184:
	s_waitcnt lgkmcnt(4)
	v_sub_f32_e32 v1, v1, v203
	v_add_f32_e32 v0, v207, v254
	v_mul_f32_e32 v1, 0x3e0293ee, v1
	v_mfma_f32_32x32x16_bf16 v[32:47], v[8:11], v[136:139], v[32:47]
	ds_read_b64_tr_b16 v[136:137], v208 offset:0x1000
	ds_read_b64_tr_b16 v[138:139], v208 offset:0x1800
	v_mfma_f32_32x32x16_bf16 v[16:31], v[8:11], v[140:143], v[16:31]
	ds_read_b64_tr_b16 v[140:141], v208 offset:0x1200
	ds_read_b64_tr_b16 v[142:143], v208 offset:0x1a00
	s_waitcnt lgkmcnt(4)
	v_fmamk_f32 v2, v80, 0x3e0293ee, v1
	v_exp_f32_e32 v2, v2
	v_fmamk_f32 v81, v81, 0x3e0293ee, v1
	v_exp_f32_e32 v159, v81
	v_add_f32_e32 v80, 0, v2
	v_add_f32_e32 v80, v159, v80
	v_mfma_f32_32x32x16_bf16 v[64:79], v[8:11], v[12:15], v[64:79]
	v_mfma_f32_32x32x16_bf16 v[48:63], v[8:11], v[132:135], v[48:63]
	s_mov_b32 m0, s97
	s_nop 0
	global_load_lds_dwordx4 v244, s[76:77]
	v_fmamk_f32 v8, v82, 0x3e0293ee, v1
	v_exp_f32_e32 v209, v8
	v_fmamk_f32 v9, v83, 0x3e0293ee, v1
	v_exp_f32_e32 v210, v9
	v_add_f32_e32 v8, v209, v80
	v_add_f32_e32 v132, v210, v8
	ds_read_b128 v[8:11], v202 offset:0x800
	ds_read_b64_tr_b16 v[12:13], v208 offset:0x1400
	ds_read_b64_tr_b16 v[14:15], v208 offset:0x1c00
	ds_read_b64_tr_b16 v[80:81], v208 offset:0x1600
	ds_read_b64_tr_b16 v[82:83], v208 offset:0x1e00
	s_waitcnt lgkmcnt(5)
	v_fmamk_f32 v84, v84, 0x3e0293ee, v1
	v_mfma_f32_32x32x16_bf16 v[16:31], v[4:7], v[140:143], v[16:31]
	v_exp_f32_e32 v140, v84
	v_fmamk_f32 v85, v85, 0x3e0293ee, v1
	v_exp_f32_e32 v141, v85
	v_add_f32_e32 v84, v140, v132
	ds_read_b64_tr_b16 v[132:133], v208 offset:0x2000
	ds_read_b64_tr_b16 v[134:135], v208 offset:0x2800
	v_mfma_f32_32x32x16_bf16 v[32:47], v[4:7], v[136:139], v[32:47]
	s_add_i32 m0, s97, 0x400
	s_nop 0
	global_load_lds_dwordx4 v245, s[76:77]
	ds_read_b64_tr_b16 v[136:137], v208 offset:0x2200
	ds_read_b64_tr_b16 v[138:139], v208 offset:0x2a00
	s_waitcnt lgkmcnt(4)
	v_add_f32_e32 v84, v141, v84
	v_mfma_f32_32x32x16_bf16 v[64:79], v[4:7], v[12:15], v[64:79]
	v_mfma_f32_32x32x16_bf16 v[48:63], v[4:7], v[80:83], v[48:63]
	s_add_i32 m0, s97, 0x4000
	s_nop 0
	global_load_lds_dwordx4 v246, s[76:77]
	v_fmamk_f32 v4, v86, 0x3e0293ee, v1
	v_exp_f32_e32 v142, v4
	v_fmamk_f32 v5, v87, 0x3e0293ee, v1
	v_exp_f32_e32 v143, v5
	v_add_f32_e32 v4, v142, v84
	v_add_f32_e32 v84, v143, v4
	ds_read_b128 v[4:7], v202 offset:0xc00
	ds_read_b64_tr_b16 v[12:13], v208 offset:0x2400
	ds_read_b64_tr_b16 v[14:15], v208 offset:0x2c00
	ds_read_b64_tr_b16 v[80:81], v208 offset:0x2600
	ds_read_b64_tr_b16 v[82:83], v208 offset:0x2e00
	s_waitcnt lgkmcnt(5)
	v_fmamk_f32 v85, v88, 0x3e0293ee, v1
	v_exp_f32_e32 v88, v85
	v_fmamk_f32 v85, v89, 0x3e0293ee, v1
	v_exp_f32_e32 v89, v85
	v_mfma_f32_32x32x16_bf16 v[32:47], v[8:11], v[132:135], v[32:47]
	v_add_f32_e32 v84, v88, v84
	v_mfma_f32_32x32x16_bf16 v[16:31], v[8:11], v[136:139], v[16:31]
	s_add_i32 m0, s97, 0x4400
	s_nop 0
	global_load_lds_dwordx4 v247, s[76:77]
	v_add_f32_e32 v136, v89, v84
	ds_read_b64_tr_b16 v[84:85], v208 offset:0x3000
	ds_read_b64_tr_b16 v[86:87], v208 offset:0x3800
	ds_read_b64_tr_b16 v[132:133], v208 offset:0x3200
	ds_read_b64_tr_b16 v[134:135], v208 offset:0x3a00
	s_waitcnt lgkmcnt(4)
	v_mfma_f32_32x32x16_bf16 v[64:79], v[8:11], v[12:15], v[64:79]
	v_mfma_f32_32x32x16_bf16 v[48:63], v[8:11], v[80:83], v[48:63]
	v_fmamk_f32 v8, v90, 0x3e0293ee, v1
	v_exp_f32_e32 v80, v8
	v_fmamk_f32 v9, v91, 0x3e0293ee, v1
	v_exp_f32_e32 v81, v9
	v_add_f32_e32 v8, v80, v136
	v_add_f32_e32 v82, v81, v8
	ds_read_b64_tr_b16 v[8:9], v208 offset:0x3400
	ds_read_b64_tr_b16 v[10:11], v208 offset:0x3c00
	ds_read_b64_tr_b16 v[12:13], v208 offset:0x3600
	ds_read_b64_tr_b16 v[14:15], v208 offset:0x3e00
	s_waitcnt lgkmcnt(4)
	v_mfma_f32_32x32x16_bf16 v[32:47], v[4:7], v[84:87], v[32:47]
	v_fmamk_f32 v83, v92, 0x3e0293ee, v1
	v_exp_f32_e32 v83, v83
	v_fmamk_f32 v84, v93, 0x3e0293ee, v1
	v_exp_f32_e32 v84, v84
	s_waitcnt lgkmcnt(0)
	v_add_f32_e32 v82, v83, v82
	v_add_f32_e32 v82, v84, v82
	v_mfma_f32_32x32x16_bf16 v[16:31], v[4:7], v[132:135], v[16:31]
	v_cvt_pk_bf16_f32 v248, v2, v159
	v_cvt_pk_bf16_f32 v249, v209, v210
	v_cvt_pk_bf16_f32 v250, v140, v141
	v_cvt_pk_bf16_f32 v251, v142, v143
	v_mfma_f32_32x32x16_bf16 v[64:79], v[4:7], v[8:11], v[64:79]
	s_add_i32 s0, s28, 1
	s_cmp_lg_u32 s28, 2
	s_cselect_b32 s1, s0, 0
	s_addk_i32 s89, 0x80
	s_add_i32 s90, s90, 2
	s_and_b64 vcc, exec, s[2:3]
	v_permlane32_swap_b32_e32 v248, v250
	v_permlane32_swap_b32_e32 v249, v251
	ds_write_b128 v205, v[248:251]
	v_fmamk_f32 v252, v94, 0x3e0293ee, v1
	v_exp_f32_e32 v253, v252
	v_fmac_f32_e32 v1, 0x3e0293ee, v95
	v_exp_f32_e32 v1, v1
	v_mfma_f32_32x32x16_bf16 v[48:63], v[4:7], v[12:15], v[48:63]
	v_add_f32_e32 v252, v253, v82
	v_add_f32_e32 v252, v1, v252
	v_add_f32_e32 v207, v0, v252
	v_cvt_pk_bf16_f32 v248, v88, v89
	v_cvt_pk_bf16_f32 v249, v80, v81
	v_cvt_pk_bf16_f32 v250, v83, v84
	v_cvt_pk_bf16_f32 v251, v253, v1
	s_nop 1
	v_permlane32_swap_b32_e32 v248, v250
	v_permlane32_swap_b32_e32 v249, v251
	ds_write_b128 v205, v[248:251] offset:1024
	s_waitcnt vmcnt(4) lgkmcnt(0)
	s_cbranch_vccnz .Lattn_exit
	s_mov_b32 s0, s88
	s_mov_b32 s29, s28
	s_mov_b32 s88, s1
	s_lshl_b32 s98, s80, 6
	s_sub_i32 s96, s89, 64
	s_sub_i32 s98, s98, 64
	s_min_i32 s96, s96, s98
	s_mul_i32 s96, s96, 0x6000
	s_lshl_b32 s97, s88, 15
	s_add_i32 s97, s83, s97
	v_add_u32_e32 v242, s96, v150
	v_add_u32_e32 v243, s96, v154
	v_add_u32_e32 v244, s96, v152
	v_add_u32_e32 v245, s96, v156
	v_add_u32_e32 v246, 0x100, v244
	v_add_u32_e32 v247, 0x100, v245
	s_branch .LBB0_172
